# seam 8 hosts an L2 warm-up of the shared cross-attention K matrix (2 MB): every workgroup touches a 64 KB slice from four idle waves before P9 starts
# baseline (speedup 1.0000x reference)
; #define SEAM(k) do { if (IN(k) && IN((k) + 1)) { if (CG_ALL || lo < 0) cg::this_grid().sync(); else xcd_barrier(xbar); } } while (0)
; __device__ __forceinline__ void xa_item(int it, LAS unsigned char* lds, const bf16_t* XQ, const bf16_t* XK, bf16_t* PB, int tid, int wid, int lane) {
;     ...
;     const bf16_t* ksrc = XK + (size_t)(b * MEML + (tid >> 4)) * 2048 + head * 512 + 8 * (tid & 15);
;     u32x4 R[8];
; #pragma unroll
;     for (int i = 0; i < 8; ++i) R[i] = *(const u32x4*)(ksrc + (size_t)(32 * i) * 2048);
; __global__ void __launch_bounds__(512, 2) mk_fwd(Args a) {
;     ...
;     SEAM(8);
;     if (IN(9)) { for (int it = bid; it < 256; it += G) xa_item(it, lds, XQ, XK, XO, tid, wid, lane); }
.Lseam_cv_8:
	s_cmp_lt_u32 s98, 2
	s_cbranch_scc1 .LBB0_1494
	s_cmp_gt_u32 s98, 5
	s_cbranch_scc1 .LBB0_1494
	s_mov_b64 exec, -1
	s_lshr_b32 s99, s87, 3
	s_lshl_b32 s99, s99, 16
	s_add_i32 s98, s98, -2
	s_lshl_b32 s98, s98, 14
	s_add_i32 s99, s99, s98
	v_and_b32_e32 v66, 63, v1
	v_lshlrev_b32_e32 v66, 7, v66
	v_add_u32_e32 v66, s99, v66
	v_add_u32_e32 v67, 0x2000, v66
	s_add_u32 s100, s84, 0x600000
	s_addc_u32 s101, s85, 0
	global_load_dword v2, v66, s[100:101]
	global_load_dword v3, v67, s[100:101]
	s_waitcnt vmcnt(0)
